# speedup vs baseline: 1.0157x; 1.0015x over previous
.LBB0_620:
	s_and_b64 s[4:5], s[6:7], exec
	v_readlane_b32 s3, v250, 22
	s_cselect_b32 s19, s21, s31
	s_cselect_b32 s35, s20, s30
	s_cselect_b32 s12, s42, s3
	s_ashr_i32 s16, s41, 6
	s_lshl_b32 s33, s16, 5
	v_bfe_u32 v11, v214, 3, 3
	v_and_b32_e32 v6, 7, v214
	v_bfe_u32 v7, v214, 4, 2
	v_or_b32_e32 v3, s33, v11
	v_bitop3_b32 v8, v7, v214, 7 bitop3:0x78
	v_bitop3_b32 v6, v7, v6, 4 bitop3:0x36
	s_lshl_b32 s38, s12, 1
	s_ashr_i32 s13, s12, 31
	s_ashr_i32 s46, s1, s0
	v_lshlrev_b32_e32 v10, 4, v8
	v_mul_lo_u32 v3, v3, s38
	v_lshlrev_b32_e32 v12, 4, v6
	s_ashr_i32 s3, s2, 31
	s_lshl_b32 s4, s12, 9
	s_lshr_b64 s[0:1], s[12:13], 23
	v_cndmask_b32_e64 v5, v157, v1, s[6:7]
	v_cndmask_b32_e64 v4, v156, v0, s[6:7]
	v_add_u32_e32 v14, v3, v10
	v_add_u32_e32 v6, v12, v3
	s_mul_i32 s1, s0, s2
	s_mul_i32 s10, s4, s3
	v_mov_b32_e32 v3, s2
	s_add_i32 s1, s10, s1
	v_mad_u64_u32 v[8:9], s[10:11], s4, v3, v[4:5]
	s_ashr_i32 s47, s46, 31
	v_add_u32_e32 v9, s1, v9
	s_mul_i32 s1, s4, s47
	s_mul_hi_u32 s10, s4, s46
	s_mul_i32 s0, s0, s46
	s_add_i32 s1, s10, s1
	s_and_b32 s97, s16, 3
	s_ashr_i32 s5, s12, 6
	s_add_i32 s1, s1, s0
	s_mul_i32 s4, s4, s46
	s_add_u32 s14, s35, s4
	s_addc_u32 s15, s19, s1
	s_ashr_i32 s0, s41, 1
	s_and_b32 s18, s0, 0xffffff80
	s_lshl_b32 s0, s16, 12
	v_mov_b32_e32 v15, v2
	s_waitcnt vmcnt(3)
	v_lshl_add_u64 v[162:163], v[8:9], 0, v[14:15]
	s_mov_b32 m0, s0
	s_lshl_b64 s[10:11], s[12:13], 4
	global_load_lds_dwordx4 v[162:163], off
	s_add_i32 m0, s0, 0x8000
	s_lshl_b32 s4, s97, 6
	global_load_lds_dwordx4 v14, s[14:15]
	v_lshl_add_u64 v[16:17], v[8:9], 0, s[10:11]
	v_mov_b32_e32 v7, v2
	s_or_b32 m0, s0, 0x400
	v_lshl_add_u64 v[18:19], v[16:17], 0, v[6:7]
	s_add_u32 s16, s14, s10
	global_load_lds_dwordx4 v[18:19], off
	s_addc_u32 s17, s15, s11
	s_add_i32 m0, s0, 0x8400
	s_lshl_b64 s[44:45], s[12:13], 5
	global_load_lds_dwordx4 v6, s[16:17]
	v_lshl_add_u64 v[16:17], v[16:17], 0, s[10:11]
	s_or_b32 m0, s0, 0x800
	v_lshl_add_u64 v[18:19], v[16:17], 0, v[14:15]
	s_add_u32 s16, s16, s10
	global_load_lds_dwordx4 v[18:19], off
	s_addc_u32 s17, s17, s11
	s_add_i32 m0, s0, 0x8800
	v_lshl_add_u64 v[164:165], s[14:15], 0, v[14:15]
	global_load_lds_dwordx4 v14, s[16:17]
	v_lshl_add_u64 v[14:15], v[16:17], 0, s[10:11]
	s_or_b32 m0, s0, 0xc00
	v_lshl_add_u64 v[16:17], v[14:15], 0, v[6:7]
	s_add_u32 s16, s16, s10
	global_load_lds_dwordx4 v[16:17], off
	s_addc_u32 s17, s17, s11
	s_add_i32 m0, s0, 0x8c00
	v_lshl_add_u64 v[16:17], v[162:163], 0, s[66:67]
	global_load_lds_dwordx4 v6, s[16:17]
	s_add_i32 m0, s0, 0x10000
	s_nop 0
	global_load_lds_dwordx4 v[16:17], off
	s_add_i32 m0, s0, 0x18000
	s_sub_u32 s44, 0, s44
	v_lshl_add_u64 v[16:17], v[164:165], 0, s[66:67]
	s_subb_u32 s45, 0, s45
	global_load_lds_dwordx4 v[16:17], off
	v_lshl_add_u64 v[14:15], v[14:15], 0, s[44:45]
	s_add_i32 m0, s0, 0x10400
	v_lshl_add_u64 v[14:15], v[14:15], 0, v[6:7]
	s_add_u32 s16, s16, s44
	v_lshl_add_u64 v[14:15], v[14:15], 0, s[66:67]
	s_addc_u32 s17, s17, s45
	global_load_lds_dwordx4 v[14:15], off
	v_lshl_add_u64 v[14:15], s[16:17], 0, v[6:7]
	v_lshl_add_u64 v[14:15], v[14:15], 0, s[66:67]
	s_add_i32 m0, s0, 0x18400
	v_and_b32_e32 v3, 31, v214
	global_load_lds_dwordx4 v[14:15], off
	s_waitcnt vmcnt(4) lgkmcnt(0)
	s_barrier
	v_bfe_u32 v213, v214, 5, 1
	v_lshrrev_b32_e32 v14, 1, v214
	v_or_b32_e32 v13, s18, v3
	v_or_b32_e32 v15, s4, v3
	v_bitop3_b32 v14, v14, v213, 7 bitop3:0x6c
	v_lshlrev_b32_e32 v179, 7, v15
	v_lshlrev_b32_e32 v178, 7, v13
	v_lshlrev_b32_e32 v14, 4, v14
	v_or_b32_e32 v183, v179, v14
	v_and_b32_e32 v246, 15, v214
	v_bfe_u32 v247, v214, 4, 2
	v_and_b32_e32 v248, 3, v246
	v_and_b32_e32 v249, 4, v246
	v_lshl_or_b32 v248, v249, 1, v248
	v_and_b32_e32 v249, 8, v246
	v_lshrrev_b32_e32 v249, 1, v249
	v_or_b32_e32 v248, v248, v249
	v_lshrrev_b32_e32 v249, 1, v248
	v_xor_b32_e32 v249, v249, v247
	v_lshlrev_b32_e32 v249, 4, v249
	v_lshl_or_b32 v249, v248, 7, v249
	s_lshl_b32 s16, s18, 7
	v_or_b32_e32 v215, s16, v249
	v_lshrrev_b32_e32 v249, 1, v246
	v_xor_b32_e32 v249, v249, v247
	v_lshlrev_b32_e32 v249, 4, v249
	v_lshl_or_b32 v249, v246, 7, v249
	s_lshl_b32 s16, s4, 7
	s_or_b32 s16, s16, 0x8000
	v_or_b32_e32 v216, s16, v249
	ds_read_b128 v[132:135], v216
	ds_read_b128 v[136:139], v216 offset:2048
	ds_read_b128 v[140:143], v216 offset:4096
	ds_read_b128 v[144:147], v216 offset:6144
	ds_read_b128 v[148:151], v215
	ds_read_b128 v[152:155], v215 offset:2048
	ds_read_b128 v[238:241], v215 offset:4096
	ds_read_b128 v[242:245], v215 offset:6144
	v_bfe_u32 v13, v214, 1, 3
	v_bitop3_b32 v14, v213, v13, 4 bitop3:0x36
	v_bitop3_b32 v15, v213, v13, 6 bitop3:0x36
	s_cmp_gt_i32 s5, 1
	s_mov_b64 s[16:17], -1
	v_lshlrev_b32_e32 v182, 4, v14
	v_lshlrev_b32_e32 v181, 4, v15
	s_cbranch_scc1 .LBB0_622
	v_lshlrev_b32_e32 v166, 4, v14
	v_lshlrev_b32_e32 v167, 4, v15
	s_mov_b64 s[16:17], 0
